# stack_i + de-serialised GEMM prologues (wait-state distance kept with s_nop) + loop-invariant B-fragment LDS base
# baseline (speedup 1.0000x reference)
; #define PG8_STAGE(bufoff, gbase, voff) do { const int so_ = (int)(unsigned)((const char*)(gbase) - base_##voff); _Pragma("unroll") for (int _i = 0; _i < 2; ++_i) \
;         __builtin_amdgcn_raw_ptr_buffer_load_lds(rs_##voff, (PG8_LAS unsigned*)(lds + (bufoff) + ldsw + _i * 8192), 16, (int)(voff)[_i], so_, 0, 0); } while (0)
; #define PG8_WAIT_V(n) asm volatile("s_waitcnt vmcnt(" #n ")" ::: "memory")
; #define PG8_BAR __builtin_amdgcn_s_barrier()
; template <class Epi, class Sched, bool ALIGN_EPI = false, bool SP2 = false>
; __device__ __forceinline__ void gemm_phase(PG8_LAS unsigned char* lds, const Gemm g, const Sched& S, const Epi& E, int tid_in) {
;     int tid_ = tid_in; asm volatile("" : "+v"(tid_)); const int tid = tid_, wid = __builtin_amdgcn_readfirstlane(tid >> 6), lane = tid & 63, wr = wid >> 2, wc = wid & 3, fr = lane & 15, fq = lane >> 4;
;     const int K = g.K, nt = K / BK;
;     unsigned voffA[2], voffB[2];
; #pragma unroll
;     for (int i = 0; i < 2; ++i) { int R, C; stage_rc(tid * 16 + i * 8192, R, C); const int Rb = Epi::PERM ? ((R & ~31) + perm32(R & 31)) : R;
;         voffA[i] = (unsigned)(R * g.lda + C) * 2u; voffB[i] = (unsigned)(Rb * g.ldb + C) * 2u; }
;     const char* const base_voffA = (const char*)g.A; const char* const base_voffB = (const char*)g.Bt;
;     const __amdgpu_buffer_rsrc_t rs_voffA = __builtin_amdgcn_make_buffer_rsrc((void*)g.A, 0, 0x7fffffff, 0x00020000), rs_voffB = __builtin_amdgcn_make_buffer_rsrc((void*)g.Bt, 0, 0x7fffffff, 0x00020000);
;     const size_t kstep = (size_t)(BK * 2);
;     const size_t hstepA = (size_t)HALF * g.lda * 2, hstepB = (size_t)HALF * g.ldb * 2;
;     const size_t tstepA = 2 * hstepA, tstepB = 2 * hstepB;
;     const unsigned ldsw = (unsigned)wid * 1024u;
;     const int aoff = lds_byte(wr * 64 + fr, fq * 8), boff = lds_byte(wc * 32 + fr, fq * 8);
;     ...
;     if constexpr (SP2) {
;         PG8_STAGE(PG8_SB(0, 0), cB, voffB); PG8_STAGE(PG8_SB(0, 1), cB + hstepB, voffB); PG8_STAGE(PG8_SA(0, 0), cA, voffA); PG8_STAGE(PG8_SA(0, 1), cA + hstepA, voffA);
;         if (wr == 1) PG8_BAR;
;         PG8_WAIT_V(2); PG8_BAR;
;         PG8_STAGE(PG8_SB(1, 0), cB + kstep, voffB); PG8_STAGE(PG8_SA(1, 0), cA + kstep, voffA); PG8_STAGE(PG8_SB(1, 1), cB + hstepB + kstep, voffB);
;         PG8_WAIT_V(6); PG8_BAR;
.LBB0_306:
	v_readlane_b32 s12, v254, 31
	v_readlane_b32 s13, v254, 32
	s_add_u32 s16, s40, s12
	s_addc_u32 s17, s60, s13
	v_readlane_b32 s12, v254, 28
	v_readlane_b32 s13, v254, 29
	s_add_u32 s12, s4, s12
	s_addc_u32 s13, s26, s13
	s_and_b32 s14, s14, 3
	s_lshl_b32 s18, s15, 13
	s_lshl_b32 s19, s14, 12
	s_add_u32 s38, s10, 0x2f500000
	s_addc_u32 s39, s11, 0
	s_add_u32 s44, s10, 0x24d00000
	v_readlane_b32 s76, v252, 0
	s_addc_u32 s45, s11, 0
	s_mul_i32 s11, s52, 0x6000
	v_readlane_b32 s84, v252, 8
	s_mul_hi_u32 s10, s52, 0x6000
	v_readlane_b32 s85, v252, 9
	s_add_u32 s46, s84, s11
	s_addc_u32 s47, s85, s10
	s_add_i32 s75, s53, 0x18000
	v_readlane_b32 s77, v252, 1
	s_mov_b32 s42, s6
	s_mov_b32 s43, s7
	s_mov_b32 m0, s75
	v_readlane_b32 s10, v254, 27
	s_add_i32 s76, s53, 0x1a000
	v_readlane_b32 s78, v252, 2
	s_nop 1
	s_add_i32 s77, s53, 0x8000
	s_nop 0
	buffer_load_dwordx4 v207, s[40:43], s10 offen lds
	s_mov_b32 m0, s76
	v_readlane_b32 s79, v252, 3
	buffer_load_dwordx4 v224, s[40:43], s10 offen lds
	s_mov_b32 m0, s77
	v_readlane_b32 s10, v254, 30
	s_add_i32 s78, s53, 0xa000
	s_add_i32 s79, s53, 0x1c000
	s_add_i32 s68, s53, 0x1e000
	v_bfe_u32 v2, v16, 4, 2
	v_and_b32_e32 v0, 15, v16
	buffer_load_dwordx4 v195, s[4:7], s10 offen lds
	s_mov_b32 m0, s78
	v_lshlrev_b32_e32 v4, 4, v2
	buffer_load_dwordx4 v211, s[4:7], s10 offen lds
	s_mov_b32 m0, s79
	v_readlane_b32 s10, v254, 33
	v_lshl_or_b32 v225, s15, 6, v0
	v_lshl_or_b32 v0, v0, 6, v4
	v_lshlrev_b32_e32 v4, 2, v16
	v_readlane_b32 s88, v252, 12
	v_readlane_b32 s89, v252, 13
	buffer_load_dwordx4 v207, s[40:43], s10 offen lds
	s_mov_b32 m0, s68
	v_lshlrev_b32_e32 v3, 3, v2
	buffer_load_dwordx4 v224, s[40:43], s10 offen lds
	v_and_b32_e32 v4, 32, v4
	s_waitcnt vmcnt(8)
	s_barrier
	s_waitcnt vmcnt(6)
	s_add_i32 s69, s53, 0xc000
	v_lshlrev_b32_e32 v2, 2, v2
	v_readlane_b32 s90, v252, 14
	v_readlane_b32 s91, v252, 15
	v_bitop3_b32 v5, v0, s18, v4 bitop3:0xde
	v_bitop3_b32 v0, v0, s19, v4 bitop3:0xde
	s_cmpk_lt_u32 s9, 0x100
	v_lshl_or_b32 v194, s14, 4, v2
	v_readlane_b32 s10, v254, 24
	v_readlane_b32 s88, v252, 54
	v_lshl_or_b32 v236, s14, 5, v3
	s_cselect_b64 s[48:49], -1, 0
	v_or_b32_e32 v206, 64, v194
	s_add_i32 s67, s53, 0xe000
	s_mov_b32 s66, 0
	v_add_u32_e32 v237, 0, v0
	v_add_u32_e32 v238, 0, v5
	v_readlane_b32 s9, v253, 55
	s_mov_b32 s18, s10
	v_readlane_b32 s89, v252, 55
	s_mov_b32 s90, s20
	s_mov_b32 s91, s21
	v_readlane_b32 s80, v252, 4
	v_readlane_b32 s81, v252, 5
	v_readlane_b32 s82, v252, 6
	v_readlane_b32 s83, v252, 7
	v_readlane_b32 s86, v252, 10
	v_readlane_b32 s87, v252, 11
	s_barrier
	v_readlane_b32 s11, v254, 25
	s_branch .LBB0_309

; #define PG8_STAGE(bufoff, gbase, voff) do { const int so_ = (int)(unsigned)((const char*)(gbase) - base_##voff); _Pragma("unroll") for (int _i = 0; _i < 2; ++_i) \
;         __builtin_amdgcn_raw_ptr_buffer_load_lds(rs_##voff, (PG8_LAS unsigned*)(lds + (bufoff) + ldsw + _i * 8192), 16, (int)(voff)[_i], so_, 0, 0); } while (0)
; #define PG8_WAIT_V(n) asm volatile("s_waitcnt vmcnt(" #n ")" ::: "memory")
; #define PG8_BAR __builtin_amdgcn_s_barrier()
; template <class Epi, class Sched, bool ALIGN_EPI = false, bool SP2 = false>
; __device__ __forceinline__ void gemm_phase(PG8_LAS unsigned char* lds, const Gemm g, const Sched& S, const Epi& E, int tid_in) {
;     ...
;     f32x4 acc[2][2][4][2];
; #pragma unroll
;     for (int a = 0; a < 2; ++a)
; #pragma unroll
;         for (int b = 0; b < 2; ++b)
; #pragma unroll
;             for (int m = 0; m < 4; ++m)
; #pragma unroll
;                 for (int n = 0; n < 2; ++n) acc[a][b][m][n] = (f32x4){0.f, 0.f, 0.f, 0.f};
;     ...
;     if constexpr (SP2) {
;         PG8_STAGE(PG8_SB(0, 0), cB, voffB); PG8_STAGE(PG8_SB(0, 1), cB + hstepB, voffB); PG8_STAGE(PG8_SA(0, 0), cA, voffA); PG8_STAGE(PG8_SA(0, 1), cA + hstepA, voffA);
;         if (wr == 1) PG8_BAR;
;         PG8_WAIT_V(2); PG8_BAR;
;         PG8_STAGE(PG8_SB(1, 0), cB + kstep, voffB); PG8_STAGE(PG8_SA(1, 0), cA + kstep, voffA); PG8_STAGE(PG8_SB(1, 1), cB + hstepB + kstep, voffB);
;         PG8_WAIT_V(6); PG8_BAR;
.LBB0_1025:
	v_readlane_b32 s10, v254, 44
	v_readlane_b32 s11, v254, 45
	s_add_u32 s16, s44, s10
	s_addc_u32 s17, s20, s11
	v_readlane_b32 s10, v254, 39
	v_readlane_b32 s24, v254, 34
	s_add_u32 s10, s4, s10
	s_mul_hi_i32 s11, s24, 0x180000
	s_addc_u32 s11, s9, s11
	v_readlane_b32 s12, v254, 37
	v_readlane_b32 s13, v254, 38
	s_add_u32 s12, s10, s12
	s_addc_u32 s13, s11, s13
	s_add_u32 s10, s14, 0x45500000
	s_addc_u32 s11, s15, 0
	s_add_u32 s67, s14, 0x2f504800
	s_addc_u32 s68, s15, 0
	s_add_i32 s69, s21, 0x18000
	s_mov_b32 s46, s6
	s_mov_b32 s47, s7
	s_mov_b32 m0, s69
	v_readlane_b32 s14, v254, 41
	s_add_i32 s71, s21, 0x1a000
	s_nop 1
	s_add_i32 s72, s21, 0x8000
	s_add_i32 s73, s21, 0xa000
	s_nop 0
	buffer_load_dwordx4 v221, s[44:47], s14 offen lds
	s_mov_b32 m0, s71
	s_add_i32 s74, s21, 0x1c000
	buffer_load_dwordx4 v223, s[44:47], s14 offen lds
	s_mov_b32 m0, s72
	v_readlane_b32 s14, v254, 43
	s_add_i32 s75, s21, 0x1e000
	v_lshrrev_b32_e32 v3, 1, v0
	v_and_b32_e32 v3, 24, v3
	v_and_b32_e32 v2, 15, v0
	v_lshlrev_b32_e32 v4, 1, v3
	buffer_load_dwordx4 v220, s[4:7], s14 offen lds
	s_mov_b32 m0, s73
	v_lshlrev_b32_e32 v0, 2, v0
	buffer_load_dwordx4 v222, s[4:7], s14 offen lds
	s_mov_b32 m0, s74
	v_readlane_b32 s14, v254, 46
	v_lshl_or_b32 v224, s22, 6, v2
	v_lshl_or_b32 v2, v2, 6, v4
	v_and_b32_e32 v0, 32, v0
	s_add_i32 s76, s21, 0xc000
	s_mov_b32 s78, 0
	buffer_load_dwordx4 v221, s[44:47], s14 offen lds
	s_mov_b32 m0, s75
	v_readlane_b32 s34, v254, 15
	buffer_load_dwordx4 v223, s[44:47], s14 offen lds
	s_lshl_b32 s14, s22, 13
	v_bitop3_b32 v4, v2, s14, v0 bitop3:0xde
	s_lshl_b32 s14, s19, 5
	s_and_b32 s19, s14, 0x60
	s_lshl_b32 s14, s19, 7
	v_bitop3_b32 v5, v2, s14, v0 bitop3:0xde
	s_waitcnt vmcnt(8)
	s_barrier
	s_waitcnt vmcnt(6)
	v_or_b32_e32 v225, s19, v3
	v_mov_b32_e32 v2, v1
	v_mov_b32_e32 v3, v1
	s_cmpk_lt_u32 s18, 0x100
	v_mov_b32_e32 v0, v1
	v_add_u32_e32 v236, 0, v5
	v_add_u32_e32 v237, 0, v4
	v_mov_b64_e32 v[6:7], v[2:3]
	v_mov_b64_e32 v[10:11], v[2:3]
	v_mov_b64_e32 v[14:15], v[2:3]
	v_mov_b64_e32 v[18:19], v[2:3]
	v_mov_b64_e32 v[22:23], v[2:3]
	v_mov_b64_e32 v[26:27], v[2:3]
	v_mov_b64_e32 v[30:31], v[2:3]
	v_mov_b64_e32 v[34:35], v[2:3]
	v_mov_b64_e32 v[38:39], v[2:3]
	v_mov_b64_e32 v[42:43], v[2:3]
	v_mov_b64_e32 v[46:47], v[2:3]
	v_mov_b64_e32 v[50:51], v[2:3]
	v_mov_b64_e32 v[54:55], v[2:3]
	v_mov_b64_e32 v[58:59], v[2:3]
	v_mov_b64_e32 v[62:63], v[2:3]
	v_mov_b64_e32 v[66:67], v[2:3]
	v_mov_b64_e32 v[70:71], v[2:3]
	v_mov_b64_e32 v[74:75], v[2:3]
	v_mov_b64_e32 v[78:79], v[2:3]
	v_mov_b64_e32 v[82:83], v[2:3]
	v_mov_b64_e32 v[86:87], v[2:3]
	v_mov_b64_e32 v[90:91], v[2:3]
	v_mov_b64_e32 v[94:95], v[2:3]
	v_mov_b64_e32 v[98:99], v[2:3]
	v_mov_b64_e32 v[102:103], v[2:3]
	v_mov_b64_e32 v[106:107], v[2:3]
	v_mov_b64_e32 v[110:111], v[2:3]
	v_mov_b64_e32 v[114:115], v[2:3]
	v_mov_b64_e32 v[118:119], v[2:3]
	v_mov_b64_e32 v[122:123], v[2:3]
	v_mov_b64_e32 v[126:127], v[2:3]
	v_mov_b64_e32 v[130:131], v[2:3]
	s_cselect_b64 s[14:15], -1, 0
	s_add_i32 s77, s21, 0xe000
	v_mov_b64_e32 v[4:5], v[0:1]
	v_mov_b64_e32 v[8:9], v[0:1]
	v_mov_b64_e32 v[12:13], v[0:1]
	v_mov_b64_e32 v[16:17], v[0:1]
	v_mov_b64_e32 v[20:21], v[0:1]
	v_mov_b64_e32 v[24:25], v[0:1]
	v_mov_b64_e32 v[28:29], v[0:1]
	v_mov_b64_e32 v[32:33], v[0:1]
	v_mov_b64_e32 v[36:37], v[0:1]
	v_mov_b64_e32 v[40:41], v[0:1]
	v_mov_b64_e32 v[44:45], v[0:1]
	v_mov_b64_e32 v[48:49], v[0:1]
	v_mov_b64_e32 v[52:53], v[0:1]
	v_mov_b64_e32 v[56:57], v[0:1]
	v_mov_b64_e32 v[60:61], v[0:1]
	v_mov_b64_e32 v[64:65], v[0:1]
	v_mov_b64_e32 v[68:69], v[0:1]
	v_mov_b64_e32 v[72:73], v[0:1]
	v_mov_b64_e32 v[76:77], v[0:1]
	v_mov_b64_e32 v[80:81], v[0:1]
	v_mov_b64_e32 v[84:85], v[0:1]
	v_mov_b64_e32 v[88:89], v[0:1]
	v_mov_b64_e32 v[92:93], v[0:1]
	v_mov_b64_e32 v[96:97], v[0:1]
	v_mov_b64_e32 v[100:101], v[0:1]
	v_mov_b64_e32 v[104:105], v[0:1]
	v_mov_b64_e32 v[108:109], v[0:1]
	v_mov_b64_e32 v[112:113], v[0:1]
	v_mov_b64_e32 v[116:117], v[0:1]
	v_mov_b64_e32 v[120:121], v[0:1]
	v_mov_b64_e32 v[124:125], v[0:1]
	v_mov_b64_e32 v[128:129], v[0:1]
	s_mov_b32 s35, s24
	v_readlane_b32 s25, v254, 35
	s_barrier
	s_branch .LBB0_1028

; #define PG8_STAGE(bufoff, gbase, voff) do { const int so_ = (int)(unsigned)((const char*)(gbase) - base_##voff); _Pragma("unroll") for (int _i = 0; _i < 2; ++_i) \
;         __builtin_amdgcn_raw_ptr_buffer_load_lds(rs_##voff, (PG8_LAS unsigned*)(lds + (bufoff) + ldsw + _i * 8192), 16, (int)(voff)[_i], so_, 0, 0); } while (0)
; #define PG8_WAIT_V(n) asm volatile("s_waitcnt vmcnt(" #n ")" ::: "memory")
; #define PG8_BAR __builtin_amdgcn_s_barrier()
; template <class Epi, class Sched, bool ALIGN_EPI = false, bool SP2 = false>
; __device__ __forceinline__ void gemm_phase(PG8_LAS unsigned char* lds, const Gemm g, const Sched& S, const Epi& E, int tid_in) {
;     ...
;     f32x4 acc[2][2][4][2];
; #pragma unroll
;     for (int a = 0; a < 2; ++a)
; #pragma unroll
;         for (int b = 0; b < 2; ++b)
; #pragma unroll
;             for (int m = 0; m < 4; ++m)
; #pragma unroll
;                 for (int n = 0; n < 2; ++n) acc[a][b][m][n] = (f32x4){0.f, 0.f, 0.f, 0.f};
;     ...
;     if constexpr (SP2) {
;         PG8_STAGE(PG8_SB(0, 0), cB, voffB); PG8_STAGE(PG8_SB(0, 1), cB + hstepB, voffB); PG8_STAGE(PG8_SA(0, 0), cA, voffA); PG8_STAGE(PG8_SA(0, 1), cA + hstepA, voffA);
;         if (wr == 1) PG8_BAR;
;         PG8_WAIT_V(2); PG8_BAR;
;         PG8_STAGE(PG8_SB(1, 0), cB + kstep, voffB); PG8_STAGE(PG8_SA(1, 0), cA + kstep, voffA); PG8_STAGE(PG8_SB(1, 1), cB + hstepB + kstep, voffB);
;         PG8_WAIT_V(6); PG8_BAR;
.LBB0_1256:
	v_readlane_b32 s12, v254, 1
	v_readlane_b32 s13, v254, 2
	s_add_u32 s12, s40, s12
	s_addc_u32 s10, s34, s13
	v_readlane_b32 s14, v253, 62
	v_readlane_b32 s15, v253, 63
	s_add_u32 s14, s4, s14
	s_addc_u32 s10, s9, s15
	v_and_b32_e32 v163, 15, v162
	v_and_b32_e32 v2, 48, v162
	v_lshlrev_b32_e32 v3, 2, v162
	s_and_b32 s26, s46, 3
	s_lshl_b32 s10, s11, 13
	v_lshl_or_b32 v2, v163, 6, v2
	v_and_b32_e32 v3, 32, v3
	v_bitop3_b32 v4, v2, s10, v3 bitop3:0xde
	s_lshl_b32 s10, s26, 12
	s_add_i32 s68, s35, 0x18000
	v_bitop3_b32 v3, v2, s10, v3 bitop3:0xde
	s_mov_b32 s42, s6
	s_mov_b32 s43, s7
	s_mov_b32 m0, s68
	v_readlane_b32 s10, v253, 61
	s_add_i32 s69, s35, 0x1a000
	s_nop 1
	s_add_i32 s71, s35, 0x8000
	s_add_i32 s72, s35, 0xa000
	s_nop 0
	buffer_load_dwordx4 v0, s[40:43], s10 offen lds
	s_mov_b32 m0, s69
	s_add_i32 s73, s35, 0x1c000
	buffer_load_dwordx4 v130, s[40:43], s10 offen lds
	s_mov_b32 m0, s71
	v_readlane_b32 s10, v254, 0
	s_add_i32 s74, s35, 0x1e000
	v_mov_b32_e32 v2, 0
	v_readlane_b32 s16, v254, 34
	s_mov_b32 s53, s27
	v_lshl_or_b32 v164, s11, 6, v163
	buffer_load_dwordx4 v0, s[4:7], s10 offen lds
	s_mov_b32 m0, s72
	s_add_i32 s75, s35, 0xc000
	buffer_load_dwordx4 v130, s[4:7], s10 offen lds
	s_mov_b32 m0, s73
	v_readlane_b32 s10, v254, 3
	s_add_i32 s76, s35, 0xe000
	s_mov_b32 s13, 0
	s_sub_i32 s77, 0, s4
	v_add_u32_e32 v131, 0, v3
	v_add_u32_e32 v132, 0, v4
	buffer_load_dwordx4 v0, s[40:43], s10 offen lds
	s_mov_b32 m0, s74
	s_mov_b32 s48, s16
	buffer_load_dwordx4 v130, s[40:43], s10 offen lds
	s_waitcnt vmcnt(8)
	s_barrier
	s_waitcnt vmcnt(6)
	v_readlane_b32 s10, v254, 15
	v_mov_b32_e32 v3, v2
	v_mov_b32_e32 v4, v2
	v_mov_b32_e32 v5, v2
	v_mov_b32_e32 v6, v2
	v_mov_b32_e32 v7, v2
	v_mov_b32_e32 v8, v2
	v_mov_b32_e32 v9, v2
	v_mov_b32_e32 v42, v2
	v_mov_b32_e32 v43, v2
	v_mov_b32_e32 v44, v2
	v_mov_b32_e32 v45, v2
	v_mov_b32_e32 v70, v2
	v_mov_b32_e32 v71, v2
	v_mov_b32_e32 v72, v2
	v_mov_b32_e32 v73, v2
	v_mov_b32_e32 v66, v2
	v_mov_b32_e32 v67, v2
	v_mov_b32_e32 v68, v2
	v_mov_b32_e32 v69, v2
	v_mov_b32_e32 v54, v2
	v_mov_b32_e32 v55, v2
	v_mov_b32_e32 v56, v2
	v_mov_b32_e32 v57, v2
	v_mov_b32_e32 v10, v2
	v_mov_b32_e32 v11, v2
	v_mov_b32_e32 v12, v2
	v_mov_b32_e32 v13, v2
	v_mov_b32_e32 v22, v2
	v_mov_b32_e32 v23, v2
	v_mov_b32_e32 v24, v2
	v_mov_b32_e32 v25, v2
	v_mov_b32_e32 v26, v2
	v_mov_b32_e32 v27, v2
	v_mov_b32_e32 v28, v2
	v_mov_b32_e32 v29, v2
	v_mov_b32_e32 v46, v2
	v_mov_b32_e32 v47, v2
	v_mov_b32_e32 v48, v2
	v_mov_b32_e32 v49, v2
	v_mov_b32_e32 v82, v2
	v_mov_b32_e32 v83, v2
	v_mov_b32_e32 v84, v2
	v_mov_b32_e32 v85, v2
	v_mov_b32_e32 v94, v2
	v_mov_b32_e32 v95, v2
	v_mov_b32_e32 v96, v2
	v_mov_b32_e32 v97, v2
	v_mov_b32_e32 v58, v2
	v_mov_b32_e32 v59, v2
	v_mov_b32_e32 v60, v2
	v_mov_b32_e32 v61, v2
	v_mov_b32_e32 v62, v2
	v_mov_b32_e32 v63, v2
	v_mov_b32_e32 v64, v2
	v_mov_b32_e32 v65, v2
	v_mov_b32_e32 v30, v2
	v_mov_b32_e32 v31, v2
	v_mov_b32_e32 v32, v2
	v_mov_b32_e32 v33, v2
	v_mov_b32_e32 v50, v2
	v_mov_b32_e32 v51, v2
	v_mov_b32_e32 v52, v2
	v_mov_b32_e32 v53, v2
	v_mov_b32_e32 v114, v2
	v_mov_b32_e32 v115, v2
	v_mov_b32_e32 v116, v2
	v_mov_b32_e32 v117, v2
	v_mov_b32_e32 v118, v2
	v_mov_b32_e32 v119, v2
	v_mov_b32_e32 v120, v2
	v_mov_b32_e32 v121, v2
	v_mov_b32_e32 v110, v2
	v_mov_b32_e32 v111, v2
	v_mov_b32_e32 v112, v2
	v_mov_b32_e32 v113, v2
	v_mov_b32_e32 v98, v2
	v_mov_b32_e32 v99, v2
	v_mov_b32_e32 v100, v2
	v_mov_b32_e32 v101, v2
	v_mov_b32_e32 v90, v2
	v_mov_b32_e32 v91, v2
	v_mov_b32_e32 v92, v2
	v_mov_b32_e32 v93, v2
	v_mov_b32_e32 v74, v2
	v_mov_b32_e32 v75, v2
	v_mov_b32_e32 v76, v2
	v_mov_b32_e32 v77, v2
	v_mov_b32_e32 v38, v2
	v_mov_b32_e32 v39, v2
	v_mov_b32_e32 v40, v2
	v_mov_b32_e32 v41, v2
	v_mov_b32_e32 v14, v2
	v_mov_b32_e32 v15, v2
	v_mov_b32_e32 v16, v2
	v_mov_b32_e32 v17, v2
	v_mov_b32_e32 v122, v2
	v_mov_b32_e32 v123, v2
	v_mov_b32_e32 v124, v2
	v_mov_b32_e32 v125, v2
	v_mov_b32_e32 v126, v2
	v_mov_b32_e32 v127, v2
	v_mov_b32_e32 v128, v2
	v_mov_b32_e32 v129, v2
	v_mov_b32_e32 v102, v2
	v_mov_b32_e32 v103, v2
	v_mov_b32_e32 v104, v2
	v_mov_b32_e32 v105, v2
	v_mov_b32_e32 v106, v2
	v_mov_b32_e32 v107, v2
	v_mov_b32_e32 v108, v2
	v_mov_b32_e32 v109, v2
	v_mov_b32_e32 v78, v2
	v_mov_b32_e32 v79, v2
	v_mov_b32_e32 v80, v2
	v_mov_b32_e32 v81, v2
	v_mov_b32_e32 v86, v2
	v_mov_b32_e32 v87, v2
	v_mov_b32_e32 v88, v2
	v_mov_b32_e32 v89, v2
	v_mov_b32_e32 v18, v2
	v_mov_b32_e32 v19, v2
	v_mov_b32_e32 v20, v2
	v_mov_b32_e32 v21, v2
	v_mov_b32_e32 v34, v2
	v_mov_b32_e32 v35, v2
	v_mov_b32_e32 v36, v2
	v_mov_b32_e32 v37, v2
	s_barrier
	v_readlane_b32 s17, v254, 35
	s_branch .LBB0_1258

; #define PG8_STAGE(bufoff, gbase, voff) do { const int so_ = (int)(unsigned)((const char*)(gbase) - base_##voff); _Pragma("unroll") for (int _i = 0; _i < 2; ++_i) \
;         __builtin_amdgcn_raw_ptr_buffer_load_lds(rs_##voff, (PG8_LAS unsigned*)(lds + (bufoff) + ldsw + _i * 8192), 16, (int)(voff)[_i], so_, 0, 0); } while (0)
; #define PG8_WAIT_V(n) asm volatile("s_waitcnt vmcnt(" #n ")" ::: "memory")
; #define PG8_BAR __builtin_amdgcn_s_barrier()
; template <class Epi, class Sched, bool ALIGN_EPI = false, bool SP2 = false>
; __device__ __forceinline__ void gemm_phase(PG8_LAS unsigned char* lds, const Gemm g, const Sched& S, const Epi& E, int tid_in) {
;     int tid_ = tid_in; asm volatile("" : "+v"(tid_)); const int tid = tid_, wid = __builtin_amdgcn_readfirstlane(tid >> 6), lane = tid & 63, wr = wid >> 2, wc = wid & 3, fr = lane & 15, fq = lane >> 4;
;     const int K = g.K, nt = K / BK;
;     unsigned voffA[2], voffB[2];
; #pragma unroll
;     for (int i = 0; i < 2; ++i) { int R, C; stage_rc(tid * 16 + i * 8192, R, C); const int Rb = Epi::PERM ? ((R & ~31) + perm32(R & 31)) : R;
;         voffA[i] = (unsigned)(R * g.lda + C) * 2u; voffB[i] = (unsigned)(Rb * g.ldb + C) * 2u; }
;     const char* const base_voffA = (const char*)g.A; const char* const base_voffB = (const char*)g.Bt;
;     const __amdgpu_buffer_rsrc_t rs_voffA = __builtin_amdgcn_make_buffer_rsrc((void*)g.A, 0, 0x7fffffff, 0x00020000), rs_voffB = __builtin_amdgcn_make_buffer_rsrc((void*)g.Bt, 0, 0x7fffffff, 0x00020000);
;     const size_t kstep = (size_t)(BK * 2);
;     const size_t hstepA = (size_t)HALF * g.lda * 2, hstepB = (size_t)HALF * g.ldb * 2;
;     const size_t tstepA = 2 * hstepA, tstepB = 2 * hstepB;
;     const unsigned ldsw = (unsigned)wid * 1024u;
;     const int aoff = lds_byte(wr * 64 + fr, fq * 8), boff = lds_byte(wc * 32 + fr, fq * 8);
;     ...
;     if constexpr (SP2) {
;         PG8_STAGE(PG8_SB(0, 0), cB, voffB); PG8_STAGE(PG8_SB(0, 1), cB + hstepB, voffB); PG8_STAGE(PG8_SA(0, 0), cA, voffA); PG8_STAGE(PG8_SA(0, 1), cA + hstepA, voffA);
;         if (wr == 1) PG8_BAR;
;         PG8_WAIT_V(2); PG8_BAR;
;         PG8_STAGE(PG8_SB(1, 0), cB + kstep, voffB); PG8_STAGE(PG8_SA(1, 0), cA + kstep, voffA); PG8_STAGE(PG8_SB(1, 1), cB + hstepB + kstep, voffB);
;         PG8_WAIT_V(6); PG8_BAR;
.LBB0_1508:
	v_readlane_b32 s16, v254, 12
	v_readlane_b32 s17, v254, 13
	s_add_u32 s38, s40, s16
	s_addc_u32 s39, s26, s17
	v_readlane_b32 s16, v254, 9
	v_readlane_b32 s17, v254, 10
	s_add_u32 s16, s4, s16
	s_addc_u32 s17, s9, s17
	s_lshl_b32 s14, s14, 5
	s_and_b32 s14, s14, 0x60
	s_lshl_b32 s15, s13, 13
	s_lshl_b32 s18, s14, 7
	s_add_u32 s0, s0, 0x47500000
	s_addc_u32 s1, s1, 0
	s_add_i32 s53, s34, 0x18000
	s_mov_b32 s42, s6
	s_mov_b32 s43, s7
	s_mov_b32 m0, s53
	v_readlane_b32 s19, v254, 8
	s_add_i32 s60, s34, 0x1a000
	s_nop 1
	s_add_i32 s61, s34, 0x8000
	s_add_i32 s62, s34, 0xa000
	s_nop 0
	buffer_load_dwordx4 v134, s[40:43], s19 offen lds
	s_mov_b32 m0, s60
	s_add_i32 s63, s34, 0x1c000
	buffer_load_dwordx4 v136, s[40:43], s19 offen lds
	s_mov_b32 m0, s61
	v_readlane_b32 s19, v254, 11
	s_add_i32 s66, s34, 0x1e000
	v_lshrrev_b32_e32 v3, 1, v64
	v_and_b32_e32 v3, 24, v3
	v_and_b32_e32 v2, 15, v64
	v_lshlrev_b32_e32 v4, 1, v3
	buffer_load_dwordx4 v0, s[4:7], s19 offen lds
	s_mov_b32 m0, s62
	v_lshl_or_b32 v137, s13, 6, v2
	buffer_load_dwordx4 v135, s[4:7], s19 offen lds
	s_mov_b32 m0, s63
	v_readlane_b32 s19, v254, 14
	v_lshl_or_b32 v2, v2, 6, v4
	v_lshlrev_b32_e32 v4, 2, v64
	v_and_b32_e32 v4, 32, v4
	s_add_i32 s67, s34, 0xc000
	v_bitop3_b32 v5, v2, s15, v4 bitop3:0xde
	buffer_load_dwordx4 v134, s[40:43], s19 offen lds
	s_mov_b32 m0, s66
	v_bitop3_b32 v2, v2, s18, v4 bitop3:0xde
	buffer_load_dwordx4 v136, s[40:43], s19 offen lds
	s_waitcnt vmcnt(8)
	s_barrier
	s_waitcnt vmcnt(6)
	s_cmpk_lt_u32 s12, 0x100
	v_or_b32_e32 v138, s14, v3
	v_readlane_b32 s14, v254, 5
	s_cselect_b64 s[12:13], -1, 0
	s_add_i32 s68, s34, 0xe000
	s_mov_b32 s69, 0
	v_add_u32_e32 v139, 0, v2
	v_add_u32_e32 v140, 0, v5
	v_readlane_b32 s71, v253, 54
	s_mov_b32 s72, s14
	s_barrier
	v_readlane_b32 s15, v254, 6
	s_branch .LBB0_1511

; #define PG8_STAGE(bufoff, gbase, voff) do { const int so_ = (int)(unsigned)((const char*)(gbase) - base_##voff); _Pragma("unroll") for (int _i = 0; _i < 2; ++_i) \
;         __builtin_amdgcn_raw_ptr_buffer_load_lds(rs_##voff, (PG8_LAS unsigned*)(lds + (bufoff) + ldsw + _i * 8192), 16, (int)(voff)[_i], so_, 0, 0); } while (0)
; #define PG8_WAIT_V(n) asm volatile("s_waitcnt vmcnt(" #n ")" ::: "memory")
; #define PG8_BAR __builtin_amdgcn_s_barrier()
; template <class Epi, class Sched, bool ALIGN_EPI = false, bool SP2 = false>
; __device__ __forceinline__ void gemm_phase(PG8_LAS unsigned char* lds, const Gemm g, const Sched& S, const Epi& E, int tid_in) {
;     ...
;     f32x4 acc[2][2][4][2];
; #pragma unroll
;     for (int a = 0; a < 2; ++a)
; #pragma unroll
;         for (int b = 0; b < 2; ++b)
; #pragma unroll
;             for (int m = 0; m < 4; ++m)
; #pragma unroll
;                 for (int n = 0; n < 2; ++n) acc[a][b][m][n] = (f32x4){0.f, 0.f, 0.f, 0.f};
;     ...
;     if constexpr (SP2) {
;         PG8_STAGE(PG8_SB(0, 0), cB, voffB); PG8_STAGE(PG8_SB(0, 1), cB + hstepB, voffB); PG8_STAGE(PG8_SA(0, 0), cA, voffA); PG8_STAGE(PG8_SA(0, 1), cA + hstepA, voffA);
;         if (wr == 1) PG8_BAR;
;         PG8_WAIT_V(2); PG8_BAR;
;         PG8_STAGE(PG8_SB(1, 0), cB + kstep, voffB); PG8_STAGE(PG8_SA(1, 0), cA + kstep, voffA); PG8_STAGE(PG8_SB(1, 1), cB + hstepB + kstep, voffB);
;         PG8_WAIT_V(6); PG8_BAR;
.LBB0_1571:
	v_readlane_b32 s10, v254, 21
	s_add_u32 s12, s40, s10
	v_readlane_b32 s10, v254, 19
	v_and_b32_e32 v163, 15, v162
	v_and_b32_e32 v2, 48, v162
	v_lshlrev_b32_e32 v3, 2, v162
	s_add_u32 s14, s4, s10
	s_and_b32 s18, s24, 3
	s_lshl_b32 s10, s11, 13
	v_lshl_or_b32 v2, v163, 6, v2
	v_and_b32_e32 v3, 32, v3
	v_bitop3_b32 v4, v2, s10, v3 bitop3:0xde
	s_lshl_b32 s10, s18, 12
	s_add_i32 s60, s19, 0x18000
	v_bitop3_b32 v3, v2, s10, v3 bitop3:0xde
	s_mov_b32 s42, s6
	s_mov_b32 s43, s7
	s_mov_b32 m0, s60
	v_readlane_b32 s10, v254, 18
	s_add_i32 s61, s19, 0x1a000
	s_nop 1
	s_add_i32 s62, s19, 0x8000
	s_add_i32 s63, s19, 0xa000
	s_nop 0
	buffer_load_dwordx4 v0, s[40:43], s10 offen lds
	s_mov_b32 m0, s61
	s_add_i32 s66, s19, 0x1c000
	buffer_load_dwordx4 v130, s[40:43], s10 offen lds
	s_mov_b32 m0, s62
	v_readlane_b32 s10, v254, 20
	s_add_i32 s67, s19, 0x1e000
	v_mov_b32_e32 v2, 0
	v_readlane_b32 s16, v254, 34
	s_mov_b32 s53, s27
	v_lshl_or_b32 v165, s11, 6, v163
	buffer_load_dwordx4 v0, s[4:7], s10 offen lds
	s_mov_b32 m0, s63
	s_add_i32 s68, s19, 0xc000
	buffer_load_dwordx4 v130, s[4:7], s10 offen lds
	s_mov_b32 m0, s66
	v_readlane_b32 s10, v254, 22
	s_add_i32 s69, s19, 0xe000
	s_mov_b32 s72, 0
	s_sub_i32 s71, 0, s4
	v_add_u32_e32 v131, 0, v3
	v_add_u32_e32 v132, 0, v4
	buffer_load_dwordx4 v0, s[40:43], s10 offen lds
	s_mov_b32 m0, s67
	s_mov_b32 s25, s16
	buffer_load_dwordx4 v130, s[40:43], s10 offen lds
	s_waitcnt vmcnt(8)
	s_barrier
	s_waitcnt vmcnt(6)
	v_readlane_b32 s10, v254, 15
	v_mov_b32_e32 v3, v2
	v_mov_b32_e32 v4, v2
	v_mov_b32_e32 v5, v2
	v_mov_b32_e32 v10, v2
	v_mov_b32_e32 v11, v2
	v_mov_b32_e32 v12, v2
	v_mov_b32_e32 v13, v2
	v_mov_b32_e32 v34, v2
	v_mov_b32_e32 v35, v2
	v_mov_b32_e32 v36, v2
	v_mov_b32_e32 v37, v2
	v_mov_b32_e32 v58, v2
	v_mov_b32_e32 v59, v2
	v_mov_b32_e32 v60, v2
	v_mov_b32_e32 v61, v2
	v_mov_b32_e32 v86, v2
	v_mov_b32_e32 v87, v2
	v_mov_b32_e32 v88, v2
	v_mov_b32_e32 v89, v2
	v_mov_b32_e32 v66, v2
	v_mov_b32_e32 v67, v2
	v_mov_b32_e32 v68, v2
	v_mov_b32_e32 v69, v2
	v_mov_b32_e32 v30, v2
	v_mov_b32_e32 v31, v2
	v_mov_b32_e32 v32, v2
	v_mov_b32_e32 v33, v2
	v_mov_b32_e32 v42, v2
	v_mov_b32_e32 v43, v2
	v_mov_b32_e32 v44, v2
	v_mov_b32_e32 v45, v2
	v_mov_b32_e32 v26, v2
	v_mov_b32_e32 v27, v2
	v_mov_b32_e32 v28, v2
	v_mov_b32_e32 v29, v2
	v_mov_b32_e32 v38, v2
	v_mov_b32_e32 v39, v2
	v_mov_b32_e32 v40, v2
	v_mov_b32_e32 v41, v2
	v_mov_b32_e32 v90, v2
	v_mov_b32_e32 v91, v2
	v_mov_b32_e32 v92, v2
	v_mov_b32_e32 v93, v2
	v_mov_b32_e32 v94, v2
	v_mov_b32_e32 v95, v2
	v_mov_b32_e32 v96, v2
	v_mov_b32_e32 v97, v2
	v_mov_b32_e32 v70, v2
	v_mov_b32_e32 v71, v2
	v_mov_b32_e32 v72, v2
	v_mov_b32_e32 v73, v2
	v_mov_b32_e32 v82, v2
	v_mov_b32_e32 v83, v2
	v_mov_b32_e32 v84, v2
	v_mov_b32_e32 v85, v2
	v_mov_b32_e32 v46, v2
	v_mov_b32_e32 v47, v2
	v_mov_b32_e32 v48, v2
	v_mov_b32_e32 v49, v2
	v_mov_b32_e32 v62, v2
	v_mov_b32_e32 v63, v2
	v_mov_b32_e32 v64, v2
	v_mov_b32_e32 v65, v2
	v_mov_b32_e32 v126, v2
	v_mov_b32_e32 v127, v2
	v_mov_b32_e32 v128, v2
	v_mov_b32_e32 v129, v2
	v_mov_b32_e32 v114, v2
	v_mov_b32_e32 v115, v2
	v_mov_b32_e32 v116, v2
	v_mov_b32_e32 v117, v2
	v_mov_b32_e32 v110, v2
	v_mov_b32_e32 v111, v2
	v_mov_b32_e32 v112, v2
	v_mov_b32_e32 v113, v2
	v_mov_b32_e32 v98, v2
	v_mov_b32_e32 v99, v2
	v_mov_b32_e32 v100, v2
	v_mov_b32_e32 v101, v2
	v_mov_b32_e32 v78, v2
	v_mov_b32_e32 v79, v2
	v_mov_b32_e32 v80, v2
	v_mov_b32_e32 v81, v2
	v_mov_b32_e32 v50, v2
	v_mov_b32_e32 v51, v2
	v_mov_b32_e32 v52, v2
	v_mov_b32_e32 v53, v2
	v_mov_b32_e32 v18, v2
	v_mov_b32_e32 v19, v2
	v_mov_b32_e32 v20, v2
	v_mov_b32_e32 v21, v2
	v_mov_b32_e32 v6, v2
	v_mov_b32_e32 v7, v2
	v_mov_b32_e32 v8, v2
	v_mov_b32_e32 v9, v2
	v_mov_b32_e32 v118, v2
	v_mov_b32_e32 v119, v2
	v_mov_b32_e32 v120, v2
	v_mov_b32_e32 v121, v2
	v_mov_b32_e32 v122, v2
	v_mov_b32_e32 v123, v2
	v_mov_b32_e32 v124, v2
	v_mov_b32_e32 v125, v2
	v_mov_b32_e32 v102, v2
	v_mov_b32_e32 v103, v2
	v_mov_b32_e32 v104, v2
	v_mov_b32_e32 v105, v2
	v_mov_b32_e32 v106, v2
	v_mov_b32_e32 v107, v2
	v_mov_b32_e32 v108, v2
	v_mov_b32_e32 v109, v2
	v_mov_b32_e32 v54, v2
	v_mov_b32_e32 v55, v2
	v_mov_b32_e32 v56, v2
	v_mov_b32_e32 v57, v2
	v_mov_b32_e32 v74, v2
	v_mov_b32_e32 v75, v2
	v_mov_b32_e32 v76, v2
	v_mov_b32_e32 v77, v2
	v_mov_b32_e32 v14, v2
	v_mov_b32_e32 v15, v2
	v_mov_b32_e32 v16, v2
	v_mov_b32_e32 v17, v2
	v_mov_b32_e32 v22, v2
	v_mov_b32_e32 v23, v2
	v_mov_b32_e32 v24, v2
	v_mov_b32_e32 v25, v2
	s_barrier
	v_readlane_b32 s17, v254, 35
	s_branch .LBB0_1573
